# P6 combine rewritten: one wave per (bh,16-row) unit on f32 MFMA 16x16x4 with LDS-DMA ring prefetch (was 8-wave readlane/fmac)
# baseline (speedup 1.0000x reference)
; #define LAS __attribute__((address_space(3)))
; __device__ __forceinline__ void phase_combine(const Params& p, LAS unsigned char* lds) {
;     ...
;     for (int bu = blockIdx.x; bu < 32 * 4; bu += G) {
;         const int bh = bu >> 2, rq = bu & 3, r0 = rq * 16 + wave * 2;
;         const float* base = ST + ((size_t)(bh * NCH) * 2) * 4096;
;         float s0 = base[(r0) * 64 + lane], s1 = base[(r0 + 1) * 64 + lane];
;         f32x4 pr0, pr1; float q0n, q1n;
;         __syncthreads();
;         { const f32x4* pp = (const f32x4*)(base + 1 * 8192 + 4096); pr0 = pp[tid]; pr1 = pp[tid + 512]; q0n = base[1 * 8192 + (r0) * 64 + lane]; q1n = base[1 * 8192 + (r0 + 1) * 64 + lane]; }
;         *(LAS f32x4*)(PL + 4096 + tid * 4) = pr0; *(LAS f32x4*)(PL + 4096 + (tid + 512) * 4) = pr1;
;         __syncthreads();
.LBB0_1134:
	s_cmp_lt_i32 s30, 7
	s_cselect_b64 s[0:1], -1, 0
	s_and_b64 s[4:5], s[0:1], s[4:5]
	s_andn2_b64 vcc, exec, s[4:5]
	s_cbranch_vccnz .LBB0_1293
	v_readlane_b32 s4, v244, 0
	v_readlane_b32 s5, v244, 1
	s_cmpk_lt_i32 s4, 0x81
	s_cselect_b64 s[4:5], -1, 0
	s_cmpk_lt_i32 s96, 0x80
	s_cselect_b64 s[6:7], -1, 0
	s_or_b64 s[6:7], s[6:7], s[4:5]
	v_and_b32_e32 v78, 63, v144
	s_mov_b64 s[4:5], -1
	s_and_b64 vcc, exec, s[6:7]
	s_cbranch_vccz .LBB0_1142
	s_cmpk_gt_i32 s96, 0x7f
	s_cbranch_scc1 .LBB0_1141
	v_readfirstlane_b32 s3, v145
	s_mov_b32 s47, s96
	s_nop 0
	s_cmp_lg_u32 s3, 0
	s_cbranch_scc1 .LBB0_1141
.Lp6_unit:
	s_lshr_b32 s4, s47, 2
	s_lshl_b32 s4, s4, 21
	s_add_u32 s6, s28, 0x38000000
	s_addc_u32 s7, s29, 0
	s_add_u32 s6, s6, s4
	s_addc_u32 s7, s7, 0
	s_and_b32 s5, s47, 3
	s_lshl_b32 s5, s5, 12
	v_and_b32_e32 v123, 63, v144
	v_lshrrev_b32_e32 v124, 4, v123
	v_and_b32_e32 v125, 15, v123
	v_lshlrev_b32_e32 v116, 12, v124
	v_lshl_add_u32 v116, v125, 4, v116
	v_add_u32_e32 v116, 0x4000, v116
	v_mov_b32_e32 v117, 0
	v_lshlrev_b32_e32 v118, 8, v125
	v_lshl_add_u32 v118, v124, 6, v118
	v_add_u32_e32 v118, s5, v118
	v_mov_b32_e32 v119, 0
	v_lshlrev_b32_e32 v123, 4, v123
	s_mov_b32 s13, 0
	s_mov_b32 s15, 0
	s_mov_b64 s[16:17], 0x100
	s_mov_b64 s[18:19], 16
	v_lshl_add_u64 v[116:117], s[6:7], 0, v[116:117]
	v_lshl_add_u64 v[118:119], s[6:7], 0, v[118:119]
	global_load_dwordx4 v[80:83], v[118:119], off
	global_load_dwordx4 v[84:87], v[118:119], off offset:16
	global_load_dwordx4 v[88:91], v[118:119], off offset:32
	global_load_dwordx4 v[92:95], v[118:119], off offset:48
	s_mov_b32 s12, 0x8000
	v_lshl_add_u64 v[112:113], s[12:13], 0, v[116:117]
	v_lshl_add_u64 v[114:115], s[12:13], 0, v[118:119]
	s_mov_b32 s9, 0x5000
	s_add_u32 m0, s9, 0x0
	s_nop 0
	global_load_lds_dwordx4 v[112:113], off
	v_lshl_add_u64 v[112:113], s[16:17], 0, v[112:113]
	s_add_u32 m0, s9, 0x400
	s_nop 0
	global_load_lds_dwordx4 v[112:113], off
	v_lshl_add_u64 v[112:113], s[16:17], 0, v[112:113]
	s_add_u32 m0, s9, 0x800
	s_nop 0
	global_load_lds_dwordx4 v[112:113], off
	v_lshl_add_u64 v[112:113], s[16:17], 0, v[112:113]
	s_add_u32 m0, s9, 0xc00
	s_nop 0
	global_load_lds_dwordx4 v[112:113], off
	v_lshl_add_u64 v[112:113], s[16:17], 0, v[112:113]
	s_add_u32 m0, s9, 0x1000
	s_nop 0
	global_load_lds_dwordx4 v[112:113], off
	v_lshl_add_u64 v[112:113], s[16:17], 0, v[112:113]
	s_add_u32 m0, s9, 0x1400
	s_nop 0
	global_load_lds_dwordx4 v[112:113], off
	v_lshl_add_u64 v[112:113], s[16:17], 0, v[112:113]
	s_add_u32 m0, s9, 0x1800
	s_nop 0
	global_load_lds_dwordx4 v[112:113], off
	v_lshl_add_u64 v[112:113], s[16:17], 0, v[112:113]
	s_add_u32 m0, s9, 0x1c00
	s_nop 0
	global_load_lds_dwordx4 v[112:113], off
	v_lshl_add_u64 v[112:113], s[16:17], 0, v[112:113]
	s_add_u32 m0, s9, 0x2000
	s_nop 0
	global_load_lds_dwordx4 v[112:113], off
	v_lshl_add_u64 v[112:113], s[16:17], 0, v[112:113]
	s_add_u32 m0, s9, 0x2400
	s_nop 0
	global_load_lds_dwordx4 v[112:113], off
	v_lshl_add_u64 v[112:113], s[16:17], 0, v[112:113]
	s_add_u32 m0, s9, 0x2800
	s_nop 0
	global_load_lds_dwordx4 v[112:113], off
	v_lshl_add_u64 v[112:113], s[16:17], 0, v[112:113]
	s_add_u32 m0, s9, 0x2c00
	s_nop 0
	global_load_lds_dwordx4 v[112:113], off
	v_lshl_add_u64 v[112:113], s[16:17], 0, v[112:113]
	s_add_u32 m0, s9, 0x3000
	s_nop 0
	global_load_lds_dwordx4 v[112:113], off
	v_lshl_add_u64 v[112:113], s[16:17], 0, v[112:113]
	s_add_u32 m0, s9, 0x3400
	s_nop 0
	global_load_lds_dwordx4 v[112:113], off
	v_lshl_add_u64 v[112:113], s[16:17], 0, v[112:113]
	s_add_u32 m0, s9, 0x3800
	s_nop 0
	global_load_lds_dwordx4 v[112:113], off
	v_lshl_add_u64 v[112:113], s[16:17], 0, v[112:113]
	s_add_u32 m0, s9, 0x3c00
	s_nop 0
	global_load_lds_dwordx4 v[112:113], off
	v_lshl_add_u64 v[112:113], s[16:17], 0, v[112:113]
	s_add_u32 m0, s9, 0x4000
	s_nop 0
	global_load_lds_dwordx4 v[114:115], off
	v_lshl_add_u64 v[114:115], s[18:19], 0, v[114:115]
	s_add_u32 m0, s9, 0x4400
	s_nop 0
	global_load_lds_dwordx4 v[114:115], off
	v_lshl_add_u64 v[114:115], s[18:19], 0, v[114:115]
	s_add_u32 m0, s9, 0x4800
	s_nop 0
	global_load_lds_dwordx4 v[114:115], off
	v_lshl_add_u64 v[114:115], s[18:19], 0, v[114:115]
	s_add_u32 m0, s9, 0x4c00
	s_nop 0
	global_load_lds_dwordx4 v[114:115], off
	v_lshl_add_u64 v[114:115], s[18:19], 0, v[114:115]
	s_mov_b32 s12, 0x10000
	v_lshl_add_u64 v[112:113], s[12:13], 0, v[116:117]
	v_lshl_add_u64 v[114:115], s[12:13], 0, v[118:119]
	s_mov_b32 s9, 0xa000
	s_add_u32 m0, s9, 0x0
	s_nop 0
	global_load_lds_dwordx4 v[112:113], off
	v_lshl_add_u64 v[112:113], s[16:17], 0, v[112:113]
	s_add_u32 m0, s9, 0x400
	s_nop 0
	global_load_lds_dwordx4 v[112:113], off
	v_lshl_add_u64 v[112:113], s[16:17], 0, v[112:113]
	s_add_u32 m0, s9, 0x800
	s_nop 0
	global_load_lds_dwordx4 v[112:113], off
	v_lshl_add_u64 v[112:113], s[16:17], 0, v[112:113]
	s_add_u32 m0, s9, 0xc00
	s_nop 0
	global_load_lds_dwordx4 v[112:113], off
	v_lshl_add_u64 v[112:113], s[16:17], 0, v[112:113]
	s_add_u32 m0, s9, 0x1000
	s_nop 0
	global_load_lds_dwordx4 v[112:113], off
	v_lshl_add_u64 v[112:113], s[16:17], 0, v[112:113]
	s_add_u32 m0, s9, 0x1400
	s_nop 0
	global_load_lds_dwordx4 v[112:113], off
	v_lshl_add_u64 v[112:113], s[16:17], 0, v[112:113]
	s_add_u32 m0, s9, 0x1800
	s_nop 0
	global_load_lds_dwordx4 v[112:113], off
	v_lshl_add_u64 v[112:113], s[16:17], 0, v[112:113]
	s_add_u32 m0, s9, 0x1c00
	s_nop 0
	global_load_lds_dwordx4 v[112:113], off
	v_lshl_add_u64 v[112:113], s[16:17], 0, v[112:113]
	s_add_u32 m0, s9, 0x2000
	s_nop 0
	global_load_lds_dwordx4 v[112:113], off
	v_lshl_add_u64 v[112:113], s[16:17], 0, v[112:113]
	s_add_u32 m0, s9, 0x2400
	s_nop 0
	global_load_lds_dwordx4 v[112:113], off
	v_lshl_add_u64 v[112:113], s[16:17], 0, v[112:113]
	s_add_u32 m0, s9, 0x2800
	s_nop 0
	global_load_lds_dwordx4 v[112:113], off
	v_lshl_add_u64 v[112:113], s[16:17], 0, v[112:113]
	s_add_u32 m0, s9, 0x2c00
	s_nop 0
	global_load_lds_dwordx4 v[112:113], off
	v_lshl_add_u64 v[112:113], s[16:17], 0, v[112:113]
	s_add_u32 m0, s9, 0x3000
	s_nop 0
	global_load_lds_dwordx4 v[112:113], off
	v_lshl_add_u64 v[112:113], s[16:17], 0, v[112:113]
	s_add_u32 m0, s9, 0x3400
	s_nop 0
	global_load_lds_dwordx4 v[112:113], off
	v_lshl_add_u64 v[112:113], s[16:17], 0, v[112:113]
	s_add_u32 m0, s9, 0x3800
	s_nop 0
	global_load_lds_dwordx4 v[112:113], off
	v_lshl_add_u64 v[112:113], s[16:17], 0, v[112:113]
	s_add_u32 m0, s9, 0x3c00
	s_nop 0
	global_load_lds_dwordx4 v[112:113], off
	v_lshl_add_u64 v[112:113], s[16:17], 0, v[112:113]
	s_add_u32 m0, s9, 0x4000
	s_nop 0
	global_load_lds_dwordx4 v[114:115], off
	v_lshl_add_u64 v[114:115], s[18:19], 0, v[114:115]
	s_add_u32 m0, s9, 0x4400
	s_nop 0
	global_load_lds_dwordx4 v[114:115], off
	v_lshl_add_u64 v[114:115], s[18:19], 0, v[114:115]
	s_add_u32 m0, s9, 0x4800
	s_nop 0
	global_load_lds_dwordx4 v[114:115], off
	v_lshl_add_u64 v[114:115], s[18:19], 0, v[114:115]
	s_add_u32 m0, s9, 0x4c00
	s_nop 0
	global_load_lds_dwordx4 v[114:115], off
	v_lshl_add_u64 v[114:115], s[18:19], 0, v[114:115]
	s_waitcnt vmcnt(20)
; #define LAS __attribute__((address_space(3)))
; __device__ __forceinline__ void phase_combine(const Params& p, LAS unsigned char* lds) {
;     ...
;         for (int c = 1; c < NCH - 1; ++c) {
;             const LAS float* Pc = PL + (c & 1) * 4096;
;             float n0 = q0n, n1 = q1n;
;             if (c + 1 < NCH - 1) { const f32x4* pp = (const f32x4*)(base + (size_t)(c + 1) * 8192 + 4096); pr0 = pp[tid]; pr1 = pp[tid + 512];
;                 q0n = base[(size_t)(c + 1) * 8192 + (r0) * 64 + lane]; q1n = base[(size_t)(c + 1) * 8192 + (r0 + 1) * 64 + lane]; }
;             float a0 = 0.f, a1 = 0.f, b0 = 0.f, b1 = 0.f;
; #pragma unroll
;             for (int k = 0; k < 64; k += 2) { const float pk0 = Pc[k * 64 + lane], pk1 = Pc[(k + 1) * 64 + lane];
;                 a0 += __int_as_float(__builtin_amdgcn_readlane(__float_as_int(s0), k)) * pk0; b0 += __int_as_float(__builtin_amdgcn_readlane(__float_as_int(s0), k + 1)) * pk1;
;                 a1 += __int_as_float(__builtin_amdgcn_readlane(__float_as_int(s1), k)) * pk0; b1 += __int_as_float(__builtin_amdgcn_readlane(__float_as_int(s1), k + 1)) * pk1; }
;             s0 = n0 + (a0 + b0); s1 = n1 + (a1 + b1);
;             float* Qc = ST + ((size_t)(bh * NCH + c) * 2) * 4096;
;             Qc[(r0) * 64 + lane] = s0; Qc[(r0 + 1) * 64 + lane] = s1;
;             if (c + 1 < NCH - 1) { LAS float* Pn = PL + ((c + 1) & 1) * 4096; *(LAS f32x4*)(Pn + tid * 4) = pr0; *(LAS f32x4*)(Pn + (tid + 512) * 4) = pr1; }
;             __syncthreads();
	v_add_u32_e32 v122, 0x5000, v123
	ds_read_b128 v[0:3], v122
	ds_read_b128 v[4:7], v122 offset:1024
	ds_read_b128 v[8:11], v122 offset:2048
	ds_read_b128 v[12:15], v122 offset:3072
	ds_read_b128 v[16:19], v122 offset:4096
	ds_read_b128 v[20:23], v122 offset:5120
	ds_read_b128 v[24:27], v122 offset:6144
	ds_read_b128 v[28:31], v122 offset:7168
	s_waitcnt lgkmcnt(0)
	ds_read_b128 v[32:35], v122 offset:8192
	ds_read_b128 v[36:39], v122 offset:9216
	ds_read_b128 v[40:43], v122 offset:10240
	ds_read_b128 v[44:47], v122 offset:11264
	ds_read_b128 v[48:51], v122 offset:12288
	ds_read_b128 v[52:55], v122 offset:13312
	ds_read_b128 v[56:59], v122 offset:14336
	ds_read_b128 v[60:63], v122 offset:15360
	s_waitcnt lgkmcnt(0)
	ds_read_b128 v[64:67], v122 offset:16384
	ds_read_b128 v[68:71], v122 offset:17408
	ds_read_b128 v[72:75], v122 offset:18432
	ds_read_b128 v[76:79], v122 offset:19456
	s_waitcnt lgkmcnt(0)
	s_mov_b32 s12, 0x18000
	v_lshl_add_u64 v[112:113], s[12:13], 0, v[116:117]
	v_lshl_add_u64 v[114:115], s[12:13], 0, v[118:119]
	s_mov_b32 s9, 0xf000
	s_add_u32 m0, s9, 0x0
	s_nop 0
	global_load_lds_dwordx4 v[112:113], off
	v_lshl_add_u64 v[112:113], s[16:17], 0, v[112:113]
	s_add_u32 m0, s9, 0x400
	s_nop 0
	global_load_lds_dwordx4 v[112:113], off
	v_lshl_add_u64 v[112:113], s[16:17], 0, v[112:113]
	s_add_u32 m0, s9, 0x800
	s_nop 0
	global_load_lds_dwordx4 v[112:113], off
	v_lshl_add_u64 v[112:113], s[16:17], 0, v[112:113]
	s_add_u32 m0, s9, 0xc00
	s_nop 0
	global_load_lds_dwordx4 v[112:113], off
	v_lshl_add_u64 v[112:113], s[16:17], 0, v[112:113]
	s_add_u32 m0, s9, 0x1000
	s_nop 0
	global_load_lds_dwordx4 v[112:113], off
	v_lshl_add_u64 v[112:113], s[16:17], 0, v[112:113]
	s_add_u32 m0, s9, 0x1400
	s_nop 0
	global_load_lds_dwordx4 v[112:113], off
	v_lshl_add_u64 v[112:113], s[16:17], 0, v[112:113]
	s_add_u32 m0, s9, 0x1800
	s_nop 0
	global_load_lds_dwordx4 v[112:113], off
	v_lshl_add_u64 v[112:113], s[16:17], 0, v[112:113]
	s_add_u32 m0, s9, 0x1c00
	s_nop 0
	global_load_lds_dwordx4 v[112:113], off
	v_lshl_add_u64 v[112:113], s[16:17], 0, v[112:113]
	s_add_u32 m0, s9, 0x2000
	s_nop 0
	global_load_lds_dwordx4 v[112:113], off
	v_lshl_add_u64 v[112:113], s[16:17], 0, v[112:113]
	s_add_u32 m0, s9, 0x2400
	s_nop 0
	global_load_lds_dwordx4 v[112:113], off
	v_lshl_add_u64 v[112:113], s[16:17], 0, v[112:113]
	s_add_u32 m0, s9, 0x2800
	s_nop 0
	global_load_lds_dwordx4 v[112:113], off
	v_lshl_add_u64 v[112:113], s[16:17], 0, v[112:113]
	s_add_u32 m0, s9, 0x2c00
	s_nop 0
	global_load_lds_dwordx4 v[112:113], off
	v_lshl_add_u64 v[112:113], s[16:17], 0, v[112:113]
	s_add_u32 m0, s9, 0x3000
	s_nop 0
	global_load_lds_dwordx4 v[112:113], off
	v_lshl_add_u64 v[112:113], s[16:17], 0, v[112:113]
	s_add_u32 m0, s9, 0x3400
	s_nop 0
	global_load_lds_dwordx4 v[112:113], off
	v_lshl_add_u64 v[112:113], s[16:17], 0, v[112:113]
	s_add_u32 m0, s9, 0x3800
	s_nop 0
	global_load_lds_dwordx4 v[112:113], off
	v_lshl_add_u64 v[112:113], s[16:17], 0, v[112:113]
	s_add_u32 m0, s9, 0x3c00
	s_nop 0
	global_load_lds_dwordx4 v[112:113], off
	v_lshl_add_u64 v[112:113], s[16:17], 0, v[112:113]
	s_add_u32 m0, s9, 0x4000
	s_nop 0
	global_load_lds_dwordx4 v[114:115], off
	v_lshl_add_u64 v[114:115], s[18:19], 0, v[114:115]
	s_add_u32 m0, s9, 0x4400
	s_nop 0
	global_load_lds_dwordx4 v[114:115], off
	v_lshl_add_u64 v[114:115], s[18:19], 0, v[114:115]
	s_add_u32 m0, s9, 0x4800
	s_nop 0
	global_load_lds_dwordx4 v[114:115], off
	v_lshl_add_u64 v[114:115], s[18:19], 0, v[114:115]
	s_add_u32 m0, s9, 0x4c00
	s_nop 0
	global_load_lds_dwordx4 v[114:115], off
	v_lshl_add_u64 v[114:115], s[18:19], 0, v[114:115]
	s_waitcnt vmcnt(0)
	s_mov_b32 s8, 1
.Lp6_chunk:
	s_add_u32 s11, s8, 3
	s_and_b32 s9, s11, 3
	s_min_u32 s11, s11, 62
	s_mul_i32 s9, s9, 0x5000
	s_add_u32 s10, s8, 1
	s_and_b32 s10, s10, 3
	s_mul_i32 s10, s10, 0x5000
	s_lshl_b32 s14, s8, 15
	s_lshl_b32 s12, s11, 15
	v_lshl_add_u64 v[112:113], s[12:13], 0, v[116:117]
	v_lshl_add_u64 v[114:115], s[12:13], 0, v[118:119]
	v_lshl_add_u64 v[120:121], s[14:15], 0, v[118:119]
	v_add_u32_e32 v122, s10, v123
	s_add_u32 m0, s9, 0x0
	v_mfma_f32_16x16x4_f32 v[96:99], v0, v80, 0
	v_mfma_f32_16x16x4_f32 v[100:103], v1, v80, 0
	v_mfma_f32_16x16x4_f32 v[104:107], v2, v80, 0
	v_mfma_f32_16x16x4_f32 v[108:111], v3, v80, 0
	s_waitcnt vmcnt(47)
	ds_read_b128 v[0:3], v122
	global_load_lds_dwordx4 v[112:113], off
	v_lshl_add_u64 v[112:113], s[16:17], 0, v[112:113]
	s_add_u32 m0, s9, 0x400
	v_mfma_f32_16x16x4_f32 v[96:99], v4, v81, v[96:99]
	v_mfma_f32_16x16x4_f32 v[100:103], v5, v81, v[100:103]
	v_mfma_f32_16x16x4_f32 v[104:107], v6, v81, v[104:107]
	v_mfma_f32_16x16x4_f32 v[108:111], v7, v81, v[108:111]
	s_waitcnt vmcnt(47)
	ds_read_b128 v[4:7], v122 offset:1024
	global_load_lds_dwordx4 v[112:113], off
	v_lshl_add_u64 v[112:113], s[16:17], 0, v[112:113]
	s_add_u32 m0, s9, 0x800
	v_mfma_f32_16x16x4_f32 v[96:99], v8, v82, v[96:99]
	v_mfma_f32_16x16x4_f32 v[100:103], v9, v82, v[100:103]
	v_mfma_f32_16x16x4_f32 v[104:107], v10, v82, v[104:107]
	v_mfma_f32_16x16x4_f32 v[108:111], v11, v82, v[108:111]
	s_waitcnt vmcnt(47)
	ds_read_b128 v[8:11], v122 offset:2048
	global_load_lds_dwordx4 v[112:113], off
	v_lshl_add_u64 v[112:113], s[16:17], 0, v[112:113]
	s_add_u32 m0, s9, 0xc00
	v_mfma_f32_16x16x4_f32 v[96:99], v12, v83, v[96:99]
	v_mfma_f32_16x16x4_f32 v[100:103], v13, v83, v[100:103]
	v_mfma_f32_16x16x4_f32 v[104:107], v14, v83, v[104:107]
	v_mfma_f32_16x16x4_f32 v[108:111], v15, v83, v[108:111]
	s_waitcnt vmcnt(47)
	ds_read_b128 v[12:15], v122 offset:3072
	global_load_lds_dwordx4 v[112:113], off
	v_lshl_add_u64 v[112:113], s[16:17], 0, v[112:113]
	s_waitcnt lgkmcnt(4)
; #define LAS __attribute__((address_space(3)))
; __device__ __forceinline__ void phase_combine(const Params& p, LAS unsigned char* lds) {
;     ...
;         for (int c = 1; c < NCH - 1; ++c) {
;             const LAS float* Pc = PL + (c & 1) * 4096;
;             float n0 = q0n, n1 = q1n;
;             if (c + 1 < NCH - 1) { const f32x4* pp = (const f32x4*)(base + (size_t)(c + 1) * 8192 + 4096); pr0 = pp[tid]; pr1 = pp[tid + 512];
;                 q0n = base[(size_t)(c + 1) * 8192 + (r0) * 64 + lane]; q1n = base[(size_t)(c + 1) * 8192 + (r0 + 1) * 64 + lane]; }
;             float a0 = 0.f, a1 = 0.f, b0 = 0.f, b1 = 0.f;
; #pragma unroll
;             for (int k = 0; k < 64; k += 2) { const float pk0 = Pc[k * 64 + lane], pk1 = Pc[(k + 1) * 64 + lane];
;                 a0 += __int_as_float(__builtin_amdgcn_readlane(__float_as_int(s0), k)) * pk0; b0 += __int_as_float(__builtin_amdgcn_readlane(__float_as_int(s0), k + 1)) * pk1;
;                 a1 += __int_as_float(__builtin_amdgcn_readlane(__float_as_int(s1), k)) * pk0; b1 += __int_as_float(__builtin_amdgcn_readlane(__float_as_int(s1), k + 1)) * pk1; }
;             s0 = n0 + (a0 + b0); s1 = n1 + (a1 + b1);
;             float* Qc = ST + ((size_t)(bh * NCH + c) * 2) * 4096;
;             Qc[(r0) * 64 + lane] = s0; Qc[(r0 + 1) * 64 + lane] = s1;
;             if (c + 1 < NCH - 1) { LAS float* Pn = PL + ((c + 1) & 1) * 4096; *(LAS f32x4*)(Pn + tid * 4) = pr0; *(LAS f32x4*)(Pn + (tid + 512) * 4) = pr1; }
;             __syncthreads();
;         }
	s_add_u32 m0, s9, 0x1000
	v_mfma_f32_16x16x4_f32 v[96:99], v16, v84, v[96:99]
	v_mfma_f32_16x16x4_f32 v[100:103], v17, v84, v[100:103]
	v_mfma_f32_16x16x4_f32 v[104:107], v18, v84, v[104:107]
	v_mfma_f32_16x16x4_f32 v[108:111], v19, v84, v[108:111]
	s_waitcnt vmcnt(47)
	ds_read_b128 v[16:19], v122 offset:4096
	global_load_lds_dwordx4 v[112:113], off
	v_lshl_add_u64 v[112:113], s[16:17], 0, v[112:113]
	s_add_u32 m0, s9, 0x1400
	v_mfma_f32_16x16x4_f32 v[96:99], v20, v85, v[96:99]
	v_mfma_f32_16x16x4_f32 v[100:103], v21, v85, v[100:103]
	v_mfma_f32_16x16x4_f32 v[104:107], v22, v85, v[104:107]
	v_mfma_f32_16x16x4_f32 v[108:111], v23, v85, v[108:111]
	s_waitcnt vmcnt(47)
	ds_read_b128 v[20:23], v122 offset:5120
	global_load_lds_dwordx4 v[112:113], off
	v_lshl_add_u64 v[112:113], s[16:17], 0, v[112:113]
	s_add_u32 m0, s9, 0x1800
	v_mfma_f32_16x16x4_f32 v[96:99], v24, v86, v[96:99]
	v_mfma_f32_16x16x4_f32 v[100:103], v25, v86, v[100:103]
	v_mfma_f32_16x16x4_f32 v[104:107], v26, v86, v[104:107]
	v_mfma_f32_16x16x4_f32 v[108:111], v27, v86, v[108:111]
	s_waitcnt vmcnt(47)
	ds_read_b128 v[24:27], v122 offset:6144
	global_load_lds_dwordx4 v[112:113], off
	v_lshl_add_u64 v[112:113], s[16:17], 0, v[112:113]
	s_add_u32 m0, s9, 0x1c00
	v_mfma_f32_16x16x4_f32 v[96:99], v28, v87, v[96:99]
	v_mfma_f32_16x16x4_f32 v[100:103], v29, v87, v[100:103]
	v_mfma_f32_16x16x4_f32 v[104:107], v30, v87, v[104:107]
	v_mfma_f32_16x16x4_f32 v[108:111], v31, v87, v[108:111]
	s_waitcnt vmcnt(47)
	ds_read_b128 v[28:31], v122 offset:7168
	global_load_lds_dwordx4 v[112:113], off
	v_lshl_add_u64 v[112:113], s[16:17], 0, v[112:113]
	s_waitcnt lgkmcnt(8)
	s_add_u32 m0, s9, 0x2000
	v_mfma_f32_16x16x4_f32 v[96:99], v32, v88, v[96:99]
	v_mfma_f32_16x16x4_f32 v[100:103], v33, v88, v[100:103]
	v_mfma_f32_16x16x4_f32 v[104:107], v34, v88, v[104:107]
	v_mfma_f32_16x16x4_f32 v[108:111], v35, v88, v[108:111]
	s_waitcnt vmcnt(47)
	ds_read_b128 v[32:35], v122 offset:8192
	global_load_lds_dwordx4 v[112:113], off
	v_lshl_add_u64 v[112:113], s[16:17], 0, v[112:113]
	s_add_u32 m0, s9, 0x2400
	v_mfma_f32_16x16x4_f32 v[96:99], v36, v89, v[96:99]
	v_mfma_f32_16x16x4_f32 v[100:103], v37, v89, v[100:103]
	v_mfma_f32_16x16x4_f32 v[104:107], v38, v89, v[104:107]
	v_mfma_f32_16x16x4_f32 v[108:111], v39, v89, v[108:111]
	s_waitcnt vmcnt(47)
	ds_read_b128 v[36:39], v122 offset:9216
	global_load_lds_dwordx4 v[112:113], off
	v_lshl_add_u64 v[112:113], s[16:17], 0, v[112:113]
	s_add_u32 m0, s9, 0x2800
	v_mfma_f32_16x16x4_f32 v[96:99], v40, v90, v[96:99]
	v_mfma_f32_16x16x4_f32 v[100:103], v41, v90, v[100:103]
	v_mfma_f32_16x16x4_f32 v[104:107], v42, v90, v[104:107]
	v_mfma_f32_16x16x4_f32 v[108:111], v43, v90, v[108:111]
	s_waitcnt vmcnt(47)
	ds_read_b128 v[40:43], v122 offset:10240
	global_load_lds_dwordx4 v[112:113], off
	v_lshl_add_u64 v[112:113], s[16:17], 0, v[112:113]
	s_add_u32 m0, s9, 0x2c00
	v_mfma_f32_16x16x4_f32 v[96:99], v44, v91, v[96:99]
	v_mfma_f32_16x16x4_f32 v[100:103], v45, v91, v[100:103]
	v_mfma_f32_16x16x4_f32 v[104:107], v46, v91, v[104:107]
	v_mfma_f32_16x16x4_f32 v[108:111], v47, v91, v[108:111]
	s_waitcnt vmcnt(47)
	ds_read_b128 v[44:47], v122 offset:11264
	global_load_lds_dwordx4 v[112:113], off
	v_lshl_add_u64 v[112:113], s[16:17], 0, v[112:113]
	s_waitcnt lgkmcnt(8)
	s_add_u32 m0, s9, 0x3000
	v_mfma_f32_16x16x4_f32 v[96:99], v48, v92, v[96:99]
	v_mfma_f32_16x16x4_f32 v[100:103], v49, v92, v[100:103]
	v_mfma_f32_16x16x4_f32 v[104:107], v50, v92, v[104:107]
	v_mfma_f32_16x16x4_f32 v[108:111], v51, v92, v[108:111]
	s_waitcnt vmcnt(47)
	ds_read_b128 v[48:51], v122 offset:12288
	global_load_lds_dwordx4 v[112:113], off
	v_lshl_add_u64 v[112:113], s[16:17], 0, v[112:113]
	s_add_u32 m0, s9, 0x3400
	v_mfma_f32_16x16x4_f32 v[96:99], v52, v93, v[96:99]
	v_mfma_f32_16x16x4_f32 v[100:103], v53, v93, v[100:103]
	v_mfma_f32_16x16x4_f32 v[104:107], v54, v93, v[104:107]
	v_mfma_f32_16x16x4_f32 v[108:111], v55, v93, v[108:111]
	s_waitcnt vmcnt(47)
	ds_read_b128 v[52:55], v122 offset:13312
	global_load_lds_dwordx4 v[112:113], off
	v_lshl_add_u64 v[112:113], s[16:17], 0, v[112:113]
	s_add_u32 m0, s9, 0x3800
	v_mfma_f32_16x16x4_f32 v[96:99], v56, v94, v[96:99]
	v_mfma_f32_16x16x4_f32 v[100:103], v57, v94, v[100:103]
	v_mfma_f32_16x16x4_f32 v[104:107], v58, v94, v[104:107]
	v_mfma_f32_16x16x4_f32 v[108:111], v59, v94, v[108:111]
	s_waitcnt vmcnt(47)
	ds_read_b128 v[56:59], v122 offset:14336
	global_load_lds_dwordx4 v[112:113], off
	v_lshl_add_u64 v[112:113], s[16:17], 0, v[112:113]
	s_add_u32 m0, s9, 0x3c00
	v_mfma_f32_16x16x4_f32 v[96:99], v60, v95, v[96:99]
	v_mfma_f32_16x16x4_f32 v[100:103], v61, v95, v[100:103]
	v_mfma_f32_16x16x4_f32 v[104:107], v62, v95, v[104:107]
	v_mfma_f32_16x16x4_f32 v[108:111], v63, v95, v[108:111]
	s_waitcnt vmcnt(47)
	ds_read_b128 v[60:63], v122 offset:15360
	global_load_lds_dwordx4 v[112:113], off
	v_lshl_add_u64 v[112:113], s[16:17], 0, v[112:113]
	s_waitcnt lgkmcnt(8)
	s_nop 7
	s_nop 7
	v_add_f32_e32 v80, v96, v64
	v_add_f32_e32 v81, v100, v65
	v_add_f32_e32 v82, v104, v66
	v_add_f32_e32 v83, v108, v67
	v_add_f32_e32 v84, v97, v68
	v_add_f32_e32 v85, v101, v69
	v_add_f32_e32 v86, v105, v70
	v_add_f32_e32 v87, v109, v71
	v_add_f32_e32 v88, v98, v72
	v_add_f32_e32 v89, v102, v73
	v_add_f32_e32 v90, v106, v74
	v_add_f32_e32 v91, v110, v75
	v_add_f32_e32 v92, v99, v76
	v_add_f32_e32 v93, v103, v77
	v_add_f32_e32 v94, v107, v78
	v_add_f32_e32 v95, v111, v79
	global_store_dwordx4 v[120:121], v[80:83], off
	global_store_dwordx4 v[120:121], v[84:87], off offset:16
	global_store_dwordx4 v[120:121], v[88:91], off offset:32
	global_store_dwordx4 v[120:121], v[92:95], off offset:48
	s_add_u32 m0, s9, 0x4000
	s_waitcnt vmcnt(47)
	ds_read_b128 v[64:67], v122 offset:16384
	global_load_lds_dwordx4 v[114:115], off
	v_lshl_add_u64 v[114:115], s[18:19], 0, v[114:115]
	s_add_u32 m0, s9, 0x4400
	s_waitcnt vmcnt(47)
	ds_read_b128 v[68:71], v122 offset:17408
	global_load_lds_dwordx4 v[114:115], off
	v_lshl_add_u64 v[114:115], s[18:19], 0, v[114:115]
	s_add_u32 m0, s9, 0x4800
	s_waitcnt vmcnt(47)
	ds_read_b128 v[72:75], v122 offset:18432
	global_load_lds_dwordx4 v[114:115], off
	v_lshl_add_u64 v[114:115], s[18:19], 0, v[114:115]
	s_add_u32 m0, s9, 0x4c00
	s_waitcnt vmcnt(47)
	ds_read_b128 v[76:79], v122 offset:19456
	global_load_lds_dwordx4 v[114:115], off
	v_lshl_add_u64 v[114:115], s[18:19], 0, v[114:115]
	s_waitcnt lgkmcnt(4)
	s_add_u32 s8, s8, 1
	s_cmp_lt_u32 s8, 63
	s_cbranch_scc1 .Lp6_chunk
	s_waitcnt vmcnt(0) lgkmcnt(0)
	v_readlane_b32 s4, v244, 0
	s_nop 3
	s_add_i32 s47, s47, s4
	s_cmpk_lt_i32 s47, 0x80
	s_cbranch_scc1 .Lp6_unit
